# v119 + half-step skew of waves 4-7 in the global attention loop (mid-step barrier); placement-matched
# speedup vs baseline: 1.0024x; 1.0024x over previous
.Lgo_mk:
	v_mfma_f32_32x32x16_bf16 v[80:95], v[136:139], v[100:103], v[80:95]
	v_add_f32_e32 v204, v204, v40
	v_add_f32_e32 v205, v205, v41
	v_add_f32_e32 v208, v208, v42
	v_add_f32_e32 v209, v209, v43
	v_cvt_pk_bf16_f32 v116, v40, v41
	v_cvt_pk_bf16_f32 v117, v42, v43
	v_mfma_f32_32x32x16_bf16 v[48:63], v[140:143], v[100:103], v[48:63]
	ds_read_b64_tr_b16 v[176:177], v242 offset:28672
	ds_read_b64_tr_b16 v[178:179], v242 offset:29184
	ds_read_b64_tr_b16 v[180:181], v242 offset:29696
	ds_read_b64_tr_b16 v[182:183], v242 offset:30208
	ds_read_b64_tr_b16 v[184:185], v242 offset:30720
	ds_read_b64_tr_b16 v[186:187], v242 offset:31232
	ds_read_b64_tr_b16 v[188:189], v242 offset:31744
	s_waitcnt lgkmcnt(14)
	ds_read_b64_tr_b16 v[190:191], v242 offset:32256
	v_add_f32_e32 v204, v204, v44
	v_add_f32_e32 v205, v205, v45
	v_add_f32_e32 v208, v208, v46
	v_add_f32_e32 v209, v209, v47
	v_cvt_pk_bf16_f32 v118, v44, v45
	v_cvt_pk_bf16_f32 v119, v46, v47
	v_mfma_f32_32x32x16_bf16 v[80:95], v[144:147], v[104:107], v[80:95]
	v_add_f32_e32 v204, v204, v64
	v_add_f32_e32 v205, v205, v65
	v_add_f32_e32 v208, v208, v66
	v_add_f32_e32 v209, v209, v67
	v_cvt_pk_bf16_f32 v120, v64, v65
	v_cvt_pk_bf16_f32 v121, v66, v67
	v_mfma_f32_32x32x16_bf16 v[48:63], v[148:151], v[104:107], v[48:63]
	v_add_f32_e32 v204, v204, v68
	v_add_f32_e32 v205, v205, v69
	v_add_f32_e32 v208, v208, v70
	v_add_f32_e32 v209, v209, v71
	v_cvt_pk_bf16_f32 v122, v68, v69
	v_cvt_pk_bf16_f32 v123, v70, v71
	s_add_i32 s96, s7, 1
	s_cmp_lt_i32 s96, s71
	s_cbranch_scc0 .Lgo_mv
	s_mul_hi_u32 s80, s96, 0x55555556
	s_mul_i32 s80, s80, 3
	s_sub_u32 s80, s96, s80
	s_lshl_b32 s81, s80, 13
	s_cmp_eq_u32 s80, 2
	s_cselect_b32 s81, 0x6000, s81
	s_add_i32 s81, s81, 0x6000
	s_add_i32 s81, s81, s100
	s_mov_b32 m0, s81
	s_nop 0
	global_load_lds_dwordx4 v[246:247], off
	v_lshl_add_u64 v[246:247], v[246:247], 0, s[98:99]
.Lgo_mv:
	v_mfma_f32_32x32x16_bf16 v[80:95], v[152:155], v[108:111], v[80:95]
	v_add_f32_e32 v204, v204, v72
	v_add_f32_e32 v205, v205, v73
	v_add_f32_e32 v208, v208, v74
	v_add_f32_e32 v209, v209, v75
	v_cvt_pk_bf16_f32 v124, v72, v73
	v_cvt_pk_bf16_f32 v125, v74, v75
	v_mfma_f32_32x32x16_bf16 v[48:63], v[156:159], v[108:111], v[48:63]
	v_add_f32_e32 v204, v204, v76
	v_add_f32_e32 v205, v205, v77
	v_add_f32_e32 v208, v208, v78
	v_add_f32_e32 v209, v209, v79
	v_cvt_pk_bf16_f32 v126, v76, v77
	v_cvt_pk_bf16_f32 v127, v78, v79
	s_cmp_lt_u32 s100, 0x1000
	s_cbranch_scc1 .Lgo_ms
	s_waitcnt lgkmcnt(0)
	s_and_b64 vcc, exec, s[82:83]
	s_cbranch_vccz .Lgo_m0
	s_waitcnt vmcnt(2)
	s_branch .Lgo_m1

.Lge_mk:
	v_mfma_f32_32x32x16_bf16 v[32:47], v[136:139], v[100:103], v[32:47]
	v_add_f32_e32 v204, v204, v88
	v_add_f32_e32 v205, v205, v89
	v_add_f32_e32 v208, v208, v90
	v_add_f32_e32 v209, v209, v91
	v_cvt_pk_bf16_f32 v116, v88, v89
	v_cvt_pk_bf16_f32 v117, v90, v91
	v_mfma_f32_32x32x16_bf16 v[64:79], v[140:143], v[100:103], v[64:79]
	ds_read_b64_tr_b16 v[176:177], v242 offset:28672
	ds_read_b64_tr_b16 v[178:179], v242 offset:29184
	ds_read_b64_tr_b16 v[180:181], v242 offset:29696
	ds_read_b64_tr_b16 v[182:183], v242 offset:30208
	ds_read_b64_tr_b16 v[184:185], v242 offset:30720
	ds_read_b64_tr_b16 v[186:187], v242 offset:31232
	ds_read_b64_tr_b16 v[188:189], v242 offset:31744
	s_waitcnt lgkmcnt(14)
	ds_read_b64_tr_b16 v[190:191], v242 offset:32256
	v_add_f32_e32 v204, v204, v92
	v_add_f32_e32 v205, v205, v93
	v_add_f32_e32 v208, v208, v94
	v_add_f32_e32 v209, v209, v95
	v_cvt_pk_bf16_f32 v118, v92, v93
	v_cvt_pk_bf16_f32 v119, v94, v95
	v_mfma_f32_32x32x16_bf16 v[32:47], v[144:147], v[104:107], v[32:47]
	v_add_f32_e32 v204, v204, v48
	v_add_f32_e32 v205, v205, v49
	v_add_f32_e32 v208, v208, v50
	v_add_f32_e32 v209, v209, v51
	v_cvt_pk_bf16_f32 v120, v48, v49
	v_cvt_pk_bf16_f32 v121, v50, v51
	v_mfma_f32_32x32x16_bf16 v[64:79], v[148:151], v[104:107], v[64:79]
	v_add_f32_e32 v204, v204, v52
	v_add_f32_e32 v205, v205, v53
	v_add_f32_e32 v208, v208, v54
	v_add_f32_e32 v209, v209, v55
	v_cvt_pk_bf16_f32 v122, v52, v53
	v_cvt_pk_bf16_f32 v123, v54, v55
	s_add_i32 s96, s7, 1
	s_cmp_lt_i32 s96, s71
	s_cbranch_scc0 .Lge_mv
	s_mul_hi_u32 s80, s96, 0x55555556
	s_mul_i32 s80, s80, 3
	s_sub_u32 s80, s96, s80
	s_lshl_b32 s81, s80, 13
	s_cmp_eq_u32 s80, 2
	s_cselect_b32 s81, 0x6000, s81
	s_add_i32 s81, s81, 0x6000
	s_add_i32 s81, s81, s100
	s_mov_b32 m0, s81
	s_nop 0
	global_load_lds_dwordx4 v[246:247], off
	v_lshl_add_u64 v[246:247], v[246:247], 0, s[98:99]
.Lge_mv:
	v_mfma_f32_32x32x16_bf16 v[32:47], v[152:155], v[108:111], v[32:47]
	v_add_f32_e32 v204, v204, v56
	v_add_f32_e32 v205, v205, v57
	v_add_f32_e32 v208, v208, v58
	v_add_f32_e32 v209, v209, v59
	v_cvt_pk_bf16_f32 v124, v56, v57
	v_cvt_pk_bf16_f32 v125, v58, v59
	v_mfma_f32_32x32x16_bf16 v[64:79], v[156:159], v[108:111], v[64:79]
	v_add_f32_e32 v204, v204, v60
	v_add_f32_e32 v205, v205, v61
	v_add_f32_e32 v208, v208, v62
	v_add_f32_e32 v209, v209, v63
	v_cvt_pk_bf16_f32 v126, v60, v61
	v_cvt_pk_bf16_f32 v127, v62, v63
	s_cmp_lt_u32 s100, 0x1000
	s_cbranch_scc1 .Lge_ms
	s_waitcnt lgkmcnt(0)
	s_and_b64 vcc, exec, s[82:83]
	s_cbranch_vccz .Lge_m0
	s_waitcnt vmcnt(2)
	s_branch .Lge_m1

; #define ATT_LAS __attribute__((address_space(3)))
; __device__ __forceinline__ void attn_unit(int uv, const float* sink_l, const bf16_t* P, bf16_t* Y, ATT_LAS unsigned char* lds, const float* rpb_l, const float* qn_l, const float* kn_l) {
;     ...
;     float m, lsum = 0.f; f32x16 o0 = {}, o1 = {};
;     ...
;     if (a.mode != 0 && nlat > 0) {
;         u32x4 kreg, vreg;
;         { const size_t ro = (size_t)ATT_TROW(4) * PITCH; kreg = *(const u32x4*)(kg + ro); vreg = *(const u32x4*)(vg + ro); }
;         *(ATT_LAS u32x4*)(ATT_KBUF(0) + koff) = kreg; *(ATT_LAS u32x4*)(ATT_VBUF(0) + voff) = vreg;
;         __syncthreads();
;         const int qw = a.qpos0 + 32 * wid, qr = qw >> 6;
.Lg_done:
	v_add_f32_e32 v204, v204, v205
	v_add_f32_e32 v208, v208, v209
	v_add_f32_e32 v124, v204, v208
	s_waitcnt lgkmcnt(0)
	s_barrier
	s_branch .LBB0_535
	s_nop 0
	s_nop 0
	s_nop 0
	s_nop 0
	s_nop 0
	s_nop 0
	s_nop 0
	s_nop 0
	s_nop 0
	s_nop 0
	s_nop 0
	s_nop 0
	s_nop 0
	s_nop 0
	s_nop 0
	s_nop 0
	s_nop 0
	s_nop 0
	s_nop 0
	s_nop 0
	s_nop 0
	s_nop 0
	s_nop 0
	s_nop 0
	s_nop 0
	s_nop 0
.Lmk_entry:
	v_mov_b32_e32 v202, v216
	v_mov_b32_e32 v124, 0
	v_mov_b32_e32 v0, 0
	v_mov_b32_e32 v1, 0
	v_mov_b32_e32 v2, 0
	v_mov_b32_e32 v3, 0
	v_mov_b32_e32 v4, 0
	v_mov_b32_e32 v5, 0
	v_mov_b32_e32 v6, 0
	v_mov_b32_e32 v7, 0
	v_mov_b32_e32 v8, 0
	v_mov_b32_e32 v9, 0
	v_mov_b32_e32 v10, 0
	v_mov_b32_e32 v11, 0
	v_mov_b32_e32 v12, 0
	v_mov_b32_e32 v13, 0
	v_mov_b32_e32 v14, 0
	v_mov_b32_e32 v15, 0
	v_mov_b32_e32 v16, 0
	v_mov_b32_e32 v17, 0
	v_mov_b32_e32 v18, 0
	v_mov_b32_e32 v19, 0
	v_mov_b32_e32 v20, 0
	v_mov_b32_e32 v21, 0
	v_mov_b32_e32 v22, 0
	v_mov_b32_e32 v23, 0
	v_mov_b32_e32 v24, 0
	v_mov_b32_e32 v25, 0
	v_mov_b32_e32 v26, 0
	v_mov_b32_e32 v27, 0
	v_mov_b32_e32 v28, 0
	v_mov_b32_e32 v29, 0
	v_mov_b32_e32 v30, 0
	v_mov_b32_e32 v31, 0
	s_xor_b64 s[2:3], s[24:25], -1
	s_branch .Lmk_pre
